# ln_mod loop: modulation rows reloaded only when the batch index changes (8 fewer loads on other iterations), +1 folded via a scalar 0/1 addend
# speedup vs baseline: 1.0050x; 1.0050x over previous
.LBB0_376:
	s_andn2_b64 vcc, exec, s[42:43]
	s_mov_b64 s[0:1], 0
	s_cbranch_vccnz .LBB0_517
	s_cmp_gt_i32 s10, 0
	s_mov_b64 s[22:23], -1
	s_cbranch_scc0 .LBB0_515
	v_mov_b32_e32 v0, v228
	v_readlane_b32 s0, v251, 20
	v_ashrrev_i32_e32 v3, 6, v0
	s_nop 0
	v_add_u32_e32 v2, s0, v3
	s_mov_b32 s0, 0x8800
	v_cmp_gt_i32_e32 vcc, s0, v2
	s_and_saveexec_b64 s[0:1], vcc
	s_cbranch_execz .LBB0_385
	v_lshlrev_b32_e32 v0, 2, v0
	v_and_b32_e32 v4, 64, v238
	v_and_b32_e32 v10, 0xfc, v0
	v_xor_b32_e32 v0, 16, v238
	v_add_u32_e32 v4, 64, v4
	v_cmp_lt_i32_e32 vcc, v0, v4
	v_readlane_b32 s22, v251, 15
	v_readlane_b32 s23, v251, 16
	v_cndmask_b32_e32 v0, v238, v0, vcc
	v_lshlrev_b32_e32 v21, 2, v0
	v_xor_b32_e32 v0, 32, v238
	v_cmp_lt_i32_e32 vcc, v0, v4
	v_readlane_b32 s2, v254, 10
	s_nop 0
	v_cndmask_b32_e32 v0, v238, v0, vcc
	v_lshlrev_b32_e32 v26, 2, v0
	v_lshlrev_b32_e32 v0, 2, v10
	v_lshl_add_u64 v[4:5], s[22:23], 0, v[0:1]
	v_lshl_add_u64 v[6:7], s[8:9], 0, v[0:1]
	v_lshlrev_b32_e32 v0, 1, v10
	v_lshl_add_u32 v27, v3, 3, s2
	v_readlane_b32 s2, v254, 6
	v_lshl_add_u64 v[8:9], s[96:97], 0, v[0:1]
	s_mov_b64 s[22:23], 0
	v_lshl_add_u32 v28, v3, 9, s2
	v_lshlrev_b32_e32 v0, 2, v10
	s_mov_b32 s24, -1
	v_writelane_b32 v255, s24, 27
	s_branch .LBB0_381
.LBB0_380:
	s_or_b64 exec, exec, s[26:27]
	v_and_b32_e32 v13, 0x7e00, v27
	v_and_b32_e32 v12, 0x7e00, v28
	v_lshl_add_u64 v[38:39], v[10:11], 0, v[0:1]
	v_lshlrev_b32_e32 v10, 2, v13
	v_mov_b32_e32 v11, v1
	v_lshl_add_u64 v[40:41], v[4:5], 0, v[10:11]
	v_lshlrev_b32_e32 v10, 2, v12
	v_lshl_add_u64 v[10:11], v[6:7], 0, v[10:11]
	s_mov_b32 s2, 0x1620000
	v_add_co_u32_e32 v42, vcc, s2, v10
	v_addc_co_u32_e32 v43, vcc, 0, v11, vcc
	global_load_dwordx4 v[30:33], v[38:39], off
	global_load_dwordx4 v[34:37], v[40:41], off
	global_load_dwordx4 v[82:85], v[38:39], off offset:1024
	global_load_dwordx4 v[86:89], v[40:41], off offset:1024
	global_load_dwordx4 v[90:93], v[38:39], off offset:2048
	global_load_dwordx4 v[94:97], v[42:43], off
	global_load_dwordx4 v[12:15], v[38:39], off offset:3072
	global_load_dwordx4 v[16:19], v[42:43], off offset:1024
	v_min_i32_e32 v10, 0x8000, v2
	v_ashrrev_i32_e32 v10, 12, v10
	s_nop 0
	v_readfirstlane_b32 s2, v10
	v_readlane_b32 s25, v255, 27
	s_nop 3
	s_cmp_eq_u32 s2, s25
	s_cbranch_scc1 .Lln_nomod
	v_writelane_b32 v255, s2, 27
	v_mul_i32_i24_e32 v10, 0xc00, v10
	v_readlane_b32 s24, v252, 15
	v_ashrrev_i32_e32 v11, 31, v10
	v_readlane_b32 s25, v252, 16
	s_nop 1
	v_lshl_add_u64 v[10:11], v[10:11], 2, s[24:25]
	v_lshl_add_u64 v[98:99], v[10:11], 0, v[0:1]
	v_lshlrev_b64 v[10:11], 11, v[2:3]
	s_mov_b64 s[24:25], 0x1000
	v_lshl_add_u64 v[100:101], v[98:99], 0, s[24:25]
	v_lshl_add_u64 v[10:11], v[8:9], 0, v[10:11]
	global_load_dwordx4 v[104:107], v[100:101], off offset:1024
	global_load_dwordx4 v[108:111], v[100:101], off offset:2048
	global_load_dwordx4 v[112:115], v[100:101], off
	global_load_dwordx4 v[116:119], v[98:99], off
	global_load_dwordx4 v[120:123], v[98:99], off offset:1024
	global_load_dwordx4 v[124:127], v[100:101], off offset:3072
	global_load_dwordx4 v[128:131], v[98:99], off offset:2048
	global_load_dwordx4 v[132:135], v[98:99], off offset:3072
	s_mov_b32 s24, 1.0
	s_branch .Lln_modj
.Lln_nomod:
	v_lshlrev_b64 v[10:11], 11, v[2:3]
	v_lshl_add_u64 v[10:11], v[8:9], 0, v[10:11]
	s_mov_b32 s24, 0

.Lln_x1b:
	v_pk_fma_f32 v[22:23], v[20:21], v[36:37], v[32:33] op_sel_hi:[0,1,1]
	v_pk_fma_f32 v[24:25], v[20:21], v[34:35], v[30:31] op_sel_hi:[0,1,1]
	v_add_f32_e32 v3, 0, v24
	v_add_f32_e32 v3, v3, v25
	v_add_f32_e32 v3, v3, v22
	v_add_f32_e32 v3, v3, v23
	s_cmp_eq_u32 s24, 0
	s_cbranch_scc1 .Lln_x2a
	s_waitcnt vmcnt(12)
	s_branch .Lln_x2b
.Lln_x2a:
	s_waitcnt vmcnt(4)
.Lln_x2b:
	v_pk_fma_f32 v[58:59], v[20:21], v[88:89], v[84:85] op_sel_hi:[0,1,1]
	v_pk_fma_f32 v[60:61], v[20:21], v[86:87], v[82:83] op_sel_hi:[0,1,1]
	v_add_f32_e32 v3, v3, v60
	v_add_f32_e32 v3, v3, v61
	v_add_f32_e32 v3, v3, v58
	v_add_f32_e32 v3, v3, v59
	s_cmp_eq_u32 s24, 0
	s_cbranch_scc1 .Lln_x3a
	s_waitcnt vmcnt(10)
	s_branch .Lln_x3b

.Lln_x3b:
	v_pk_fma_f32 v[64:65], v[20:21], v[94:95], v[90:91] op_sel_hi:[0,1,1]
	v_pk_fma_f32 v[62:63], v[20:21], v[96:97], v[92:93] op_sel_hi:[0,1,1]
	v_add_f32_e32 v3, v3, v64
	v_add_f32_e32 v3, v3, v65
	v_add_f32_e32 v3, v3, v62
	v_add_f32_e32 v3, v3, v63
	s_cmp_eq_u32 s24, 0
	s_cbranch_scc1 .Lln_x4a
	s_waitcnt vmcnt(8)
	s_branch .Lln_x4b

.Lln_x4b:
	v_pk_fma_f32 v[12:13], v[20:21], v[16:17], v[12:13] op_sel_hi:[0,1,1]
	v_pk_fma_f32 v[14:15], v[20:21], v[18:19], v[14:15] op_sel_hi:[0,1,1]
	v_add_f32_e32 v3, v3, v12
	v_add_f32_e32 v3, v3, v13
	v_add_f32_e32 v3, v3, v14
	v_add_f32_e32 v3, v3, v15
	s_waitcnt vmcnt(6)
	v_pk_add_f32 v[108:109], v[108:109], s[24:25] op_sel_hi:[1,0]
	v_add_f32_dpp v3, v3, v3 quad_perm:[1,0,3,2] row_mask:0xf bank_mask:0xf bound_ctrl:1
	v_pk_add_f32 v[104:105], v[104:105], s[24:25] op_sel_hi:[1,0]
	v_pk_add_f32 v[106:107], v[106:107], s[24:25] op_sel_hi:[1,0]
	v_add_f32_dpp v3, v3, v3 quad_perm:[2,3,0,1] row_mask:0xf bank_mask:0xf bound_ctrl:1
	v_pk_add_f32 v[110:111], v[110:111], s[24:25] op_sel_hi:[1,0]
	s_waitcnt vmcnt(5)
	v_pk_add_f32 v[112:113], v[112:113], s[24:25] op_sel_hi:[1,0]
	v_add_f32_dpp v3, v3, v3 row_half_mirror row_mask:0xf bank_mask:0xf bound_ctrl:1
	v_pk_add_f32 v[114:115], v[114:115], s[24:25] op_sel_hi:[1,0]
	s_waitcnt vmcnt(2)
	v_pk_add_f32 v[124:125], v[124:125], s[24:25] op_sel_hi:[1,0]
	v_add_f32_dpp v3, v3, v3 row_mirror row_mask:0xf bank_mask:0xf bound_ctrl:1
	ds_bpermute_b32 v20, v21, v3
	s_waitcnt lgkmcnt(0)
	v_add_f32_e32 v3, v3, v20
	ds_bpermute_b32 v20, v26, v3
	s_waitcnt lgkmcnt(0)
	v_add_f32_e32 v3, v3, v20
	v_mul_f32_e32 v20, 0x3a800000, v3
	v_pk_add_f32 v[24:25], v[24:25], v[20:21] op_sel_hi:[1,0] neg_lo:[0,1] neg_hi:[0,1]
	v_pk_add_f32 v[22:23], v[22:23], v[20:21] op_sel_hi:[1,0] neg_lo:[0,1] neg_hi:[0,1]
	v_pk_mul_f32 v[66:67], v[24:25], v[24:25]
	v_pk_mul_f32 v[68:69], v[22:23], v[22:23]
	v_add_f32_e32 v3, v66, v67
	v_pk_add_f32 v[60:61], v[60:61], v[20:21] op_sel_hi:[1,0] neg_lo:[0,1] neg_hi:[0,1]
	v_add_f32_e32 v3, v68, v3
	v_pk_mul_f32 v[70:71], v[60:61], v[60:61]
	v_add_f32_e32 v3, v69, v3
	v_pk_add_f32 v[58:59], v[58:59], v[20:21] op_sel_hi:[1,0] neg_lo:[0,1] neg_hi:[0,1]
	v_add_f32_e32 v3, v70, v3
	v_pk_mul_f32 v[72:73], v[58:59], v[58:59]
	v_add_f32_e32 v3, v71, v3
	v_pk_add_f32 v[64:65], v[64:65], v[20:21] op_sel_hi:[1,0] neg_lo:[0,1] neg_hi:[0,1]
	v_add_f32_e32 v3, v72, v3
	v_pk_mul_f32 v[74:75], v[64:65], v[64:65]
	v_add_f32_e32 v3, v73, v3
	v_pk_add_f32 v[62:63], v[62:63], v[20:21] op_sel_hi:[1,0] neg_lo:[0,1] neg_hi:[0,1]
	v_add_f32_e32 v3, v74, v3
	v_pk_mul_f32 v[76:77], v[62:63], v[62:63]
	v_add_f32_e32 v3, v75, v3
	v_pk_add_f32 v[12:13], v[12:13], v[20:21] op_sel_hi:[1,0] neg_lo:[0,1] neg_hi:[0,1]
	v_add_f32_e32 v3, v76, v3
	v_pk_mul_f32 v[80:81], v[12:13], v[12:13]
	v_add_f32_e32 v3, v77, v3
	v_pk_add_f32 v[14:15], v[14:15], v[20:21] op_sel_hi:[1,0] neg_lo:[0,1] neg_hi:[0,1]
	v_add_f32_e32 v3, v80, v3
	v_pk_mul_f32 v[78:79], v[14:15], v[14:15]
	v_add_f32_e32 v3, v81, v3
	v_add_f32_e32 v3, v78, v3
	v_add_f32_e32 v3, v79, v3
	s_nop 1
	v_add_f32_dpp v3, v3, v3 quad_perm:[1,0,3,2] row_mask:0xf bank_mask:0xf bound_ctrl:1
	s_nop 1
	v_add_f32_dpp v3, v3, v3 quad_perm:[2,3,0,1] row_mask:0xf bank_mask:0xf bound_ctrl:1
	s_nop 1
	v_add_f32_dpp v3, v3, v3 row_half_mirror row_mask:0xf bank_mask:0xf bound_ctrl:1
	s_nop 1
	v_add_f32_dpp v3, v3, v3 row_mirror row_mask:0xf bank_mask:0xf bound_ctrl:1
	ds_bpermute_b32 v20, v21, v3
	s_waitcnt lgkmcnt(0)
	v_add_f32_e32 v3, v3, v20
	ds_bpermute_b32 v20, v26, v3
	s_waitcnt lgkmcnt(0)
	v_add_f32_e32 v3, v3, v20
	v_fmamk_f32 v3, v3, 0x3a800000, v230
	v_mul_f32_e32 v20, 0x4b800000, v3
	v_cmp_gt_f32_e32 vcc, s72, v3
	s_nop 1
	v_cndmask_b32_e32 v3, v3, v20, vcc
	v_rsq_f32_e32 v3, v3
	s_nop 0
	v_mul_f32_e32 v20, 0x45800000, v3
	v_cndmask_b32_e32 v20, v3, v20, vcc
	v_pk_mul_f32 v[24:25], v[24:25], v[20:21] op_sel_hi:[1,0]
	v_pk_mul_f32 v[22:23], v[22:23], v[20:21] op_sel_hi:[1,0]
	v_pk_fma_f32 v[24:25], v[112:113], v[24:25], v[116:117]
	v_pk_fma_f32 v[22:23], v[114:115], v[22:23], v[118:119]
	v_cvt_pk_bf16_f32 v24, v24, v25
	v_cvt_pk_bf16_f32 v25, v22, v23
	global_store_dwordx2 v[10:11], v[24:25], off
	v_pk_mul_f32 v[22:23], v[60:61], v[20:21] op_sel_hi:[1,0]
	v_pk_mul_f32 v[24:25], v[58:59], v[20:21] op_sel_hi:[1,0]
	v_pk_fma_f32 v[22:23], v[104:105], v[22:23], v[120:121]
	v_pk_fma_f32 v[24:25], v[106:107], v[24:25], v[122:123]
	v_cvt_pk_bf16_f32 v22, v22, v23
	v_cvt_pk_bf16_f32 v23, v24, v25
	v_pk_mul_f32 v[12:13], v[12:13], v[20:21] op_sel_hi:[1,0]
	v_readlane_b32 s2, v251, 19
	global_store_dwordx2 v[10:11], v[22:23], off offset:512
	v_pk_mul_f32 v[22:23], v[64:65], v[20:21] op_sel_hi:[1,0]
	v_pk_mul_f32 v[24:25], v[62:63], v[20:21] op_sel_hi:[1,0]
	s_waitcnt vmcnt(2)
	v_pk_fma_f32 v[12:13], v[12:13], v[124:125], v[132:133]
	v_pk_mul_f32 v[14:15], v[14:15], v[20:21] op_sel_hi:[1,0]
	v_pk_add_f32 v[48:49], v[126:127], 1.0 op_sel_hi:[1,0]
	v_add_u32_e32 v2, s2, v2
	s_mov_b32 s2, 0x87ff
	v_pk_fma_f32 v[22:23], v[108:109], v[22:23], v[128:129]
	v_pk_fma_f32 v[24:25], v[110:111], v[24:25], v[130:131]
	v_pk_fma_f32 v[14:15], v[14:15], v[48:49], v[134:135]
	v_cmp_lt_i32_e32 vcc, s2, v2
	v_readlane_b32 s2, v253, 56
	v_cvt_pk_bf16_f32 v22, v22, v23
	v_cvt_pk_bf16_f32 v23, v24, v25
	v_cvt_pk_bf16_f32 v12, v12, v13
	v_cvt_pk_bf16_f32 v13, v14, v15
	v_add_u32_e32 v27, s41, v27
	s_or_b64 s[22:23], vcc, s[22:23]
	v_add_u32_e32 v28, s2, v28
	global_store_dwordx2 v[10:11], v[22:23], off offset:1024
	global_store_dwordx2 v[10:11], v[12:13], off offset:1536
	s_andn2_b64 exec, exec, s[22:23]
	s_cbranch_execz .LBB0_385
